# baseline (speedup 1.0000x reference)
; __device__ void filt_item(const Params& p, int item) {
;     ...
;   for (int mt = wid; mt < L / 16; mt += 8) {
;     const float* hrow = H2 + (size_t)(mt * 16 + n) * 64 + quad * 8;
;     f32x4 acc = {0.f, 0.f, 0.f, 0.f};
; #pragma unroll
;     for (int ks = 0; ks < 2; ++ks) {
;       float4 a0 = *(const float4*)(hrow + ks * 32), a1 = *(const float4*)(hrow + ks * 32 + 4);
;       float hv[8] = {a0.x, a0.y, a0.z, a0.w, a1.x, a1.y, a1.z, a1.w};
;       bf16x8 ah, al;
;       split_bf16x8(hv, ah, al);
;       acc = __builtin_amdgcn_mfma_f32_16x16x32_bf16(ah, bh[ks], acc, 0, 0, 0);
;       acc = __builtin_amdgcn_mfma_f32_16x16x32_bf16(al, bh[ks], acc, 0, 0, 0);
;       acc = __builtin_amdgcn_mfma_f32_16x16x32_bf16(ah, bl[ks], acc, 0, 0, 0);
;     }
.LBB0_1313:
	global_load_dwordx4 v[18:21], v[30:31], off offset:-112
	global_load_dwordx4 v[22:25], v[30:31], off offset:-128
	global_load_dwordx4 v[176:179], v[30:31], off offset:16
	global_load_dwordx4 v[180:183], v[30:31], off
	v_cvt_f32_i32_e32 v0, v39
	s_mov_b64 s[8:9], 0
	v_mul_f32_e64 v0, v38, -v0
	s_waitcnt vmcnt(2)
	v_cvt_pk_bf16_f32 v40, v22, v23
	v_lshlrev_b32_e32 v42, 16, v40
	v_and_b32_e32 v43, 0xffff0000, v40
	v_cvt_pk_bf16_f32 v41, v24, v25
	v_pk_add_f32 v[22:23], v[22:23], v[42:43] neg_lo:[0,1] neg_hi:[0,1]
	v_lshlrev_b32_e32 v42, 16, v41
	v_and_b32_e32 v43, 0xffff0000, v41
	v_pk_add_f32 v[24:25], v[24:25], v[42:43] neg_lo:[0,1] neg_hi:[0,1]
	v_cvt_pk_bf16_f32 v42, v18, v19
	v_cvt_pk_bf16_f32 v22, v22, v23
	v_cvt_pk_bf16_f32 v23, v24, v25
	v_lshlrev_b32_e32 v24, 16, v42
	v_and_b32_e32 v25, 0xffff0000, v42
	v_cvt_pk_bf16_f32 v43, v20, v21
	v_pk_add_f32 v[18:19], v[18:19], v[24:25] neg_lo:[0,1] neg_hi:[0,1]
	s_nop 0
	v_cvt_pk_bf16_f32 v24, v18, v19
	v_lshlrev_b32_e32 v18, 16, v43
	v_and_b32_e32 v19, 0xffff0000, v43
	v_pk_add_f32 v[18:19], v[20:21], v[18:19] neg_lo:[0,1] neg_hi:[0,1]
	s_nop 0
	v_cvt_pk_bf16_f32 v25, v18, v19
	v_mfma_f32_16x16x32_bf16 v[18:21], v[40:43], v[10:13], 0
	s_nop 0
	v_mfma_f32_16x16x32_bf16 v[18:21], v[22:25], v[10:13], v[18:21]
	v_mfma_f32_16x16x32_bf16 v[18:21], v[40:43], v[14:17], v[18:21]
	s_waitcnt vmcnt(0)
	v_mov_b32_e32 v22, v176
	v_mov_b32_e32 v23, v177
	v_mov_b32_e32 v24, v178
	v_mov_b32_e32 v25, v179
	v_mov_b32_e32 v40, v180
	v_mov_b32_e32 v41, v181
	v_mov_b32_e32 v42, v182
	v_mov_b32_e32 v43, v183
	v_cvt_pk_bf16_f32 v44, v40, v41
	v_lshlrev_b32_e32 v46, 16, v44
	v_and_b32_e32 v47, 0xffff0000, v44
	v_cvt_pk_bf16_f32 v45, v42, v43
	v_pk_add_f32 v[40:41], v[40:41], v[46:47] neg_lo:[0,1] neg_hi:[0,1]
	v_lshlrev_b32_e32 v46, 16, v45
	v_and_b32_e32 v47, 0xffff0000, v45
	v_pk_add_f32 v[42:43], v[42:43], v[46:47] neg_lo:[0,1] neg_hi:[0,1]
	v_cvt_pk_bf16_f32 v46, v22, v23
	v_cvt_pk_bf16_f32 v40, v40, v41
	v_cvt_pk_bf16_f32 v41, v42, v43
	v_lshlrev_b32_e32 v42, 16, v46
	v_and_b32_e32 v43, 0xffff0000, v46
	v_cvt_pk_bf16_f32 v47, v24, v25
	v_pk_add_f32 v[22:23], v[22:23], v[42:43] neg_lo:[0,1] neg_hi:[0,1]
	s_nop 0
	v_cvt_pk_bf16_f32 v42, v22, v23
	v_lshlrev_b32_e32 v22, 16, v47
	v_and_b32_e32 v23, 0xffff0000, v47
	v_pk_add_f32 v[22:23], v[24:25], v[22:23] neg_lo:[0,1] neg_hi:[0,1]
	v_mfma_f32_16x16x32_bf16 v[18:21], v[44:47], v[2:5], v[18:21]
	v_cvt_pk_bf16_f32 v43, v22, v23
	v_mul_f32_e64 v24, |v36|, v0
	v_cmp_ngt_f32_e64 s[4:5], s94, v24
	v_mfma_f32_16x16x32_bf16 v[18:21], v[40:43], v[2:5], v[18:21]
	v_cmp_nlt_f32_e64 s[6:7], s95, v24
	v_mfma_f32_16x16x32_bf16 v[18:21], v[44:47], v[6:9], v[18:21]
	s_and_saveexec_b64 s[46:47], vcc
	s_xor_b64 s[46:47], exec, s[46:47]
	s_cbranch_execz .LBB0_1317
	v_cmp_lt_i32_e64 s[8:9], 0, v39
	s_mov_b64 s[50:51], 0
	s_and_saveexec_b64 s[90:91], s[8:9]
	s_xor_b64 s[8:9], exec, s[90:91]
	v_add_u32_e32 v0, s84, v39
	s_mov_b64 s[50:51], exec
	v_mov_b64_e32 v[22:23], v[0:1]
	s_or_b64 exec, exec, s[8:9]
	s_and_b64 s[8:9], s[50:51], exec

; __device__ void attn_item(const Params& p, int layer, int item, int dry) {
;     ...
;   const int tile = item >> 2, h = item & 3;
;   const int tok0 = tile * 128;
;   const int seq = tok0 < 32768 ? (tok0 >> 11) : 16 + ((tok0 - 32768) >> 12);
;   bf16_t* Ks = (bf16_t*)smem;
;   bf16_t* Vt = (bf16_t*)(smem + 256 * 72 * 2);
;   const bf16_t* kvs = kv + (size_t)seq * 256 * 1024;
;   for (int i = 0; i < 4; ++i) {
;     int idx = tid + 512 * i;
;     int m = idx >> 3, d0 = (idx & 7) * 8;
;     uint4 uk = *(const uint4*)(kvs + (size_t)m * 1024 + h * 64 + d0);
;     *(uint4*)(Ks + m * 72 + d0) = uk;
;     uint4 uv = *(const uint4*)(kvs + (size_t)m * 1024 + 256 + h * 64 + d0);
;     unsigned uu[4] = {uv.x, uv.y, uv.z, uv.w};
;     for (int j = 0; j < 8; ++j) Vt[(d0 + j) * 264 + m] = (bf16_t)((j & 1) ? (uu[j >> 1] >> 16) : (uu[j >> 1] & 0xffff));
;   }
.LBB0_1348:
	s_and_b64 vcc, exec, s[4:5]
	s_cbranch_vccz .LBB0_1365
	s_lshl_b32 s4, s27, 5
	s_and_b32 s6, s4, 0xffffff80
	s_addk_i32 s4, 0x8000
	s_lshr_b32 s4, s4, 12
	s_ashr_i32 s5, s27, 6
	s_add_i32 s4, s4, 16
	s_cmp_lt_i32 s6, 0x8000
	v_mov_b32_e32 v44, v208
	s_cselect_b32 s4, s5, s4
	s_ashr_i32 s5, s4, 31
	v_add_u32_e32 v10, 0x200, v44
	v_add_u32_e32 v18, 0x400, v44
	v_add_u32_e32 v26, 0x600, v44
	s_lshl_b64 s[4:5], s[4:5], 19
	v_ashrrev_i32_e32 v34, 3, v44
	v_ashrrev_i32_e32 v36, 3, v10
	v_ashrrev_i32_e32 v38, 3, v18
	v_ashrrev_i32_e32 v40, 3, v26
	s_add_u32 s4, s77, s4
	v_ashrrev_i32_e32 v35, 31, v34
	v_ashrrev_i32_e32 v37, 31, v36
	v_ashrrev_i32_e32 v39, 31, v38
	v_ashrrev_i32_e32 v41, 31, v40
	s_addc_u32 s5, s78, s5
	v_lshlrev_b32_e32 v0, 3, v44
	v_lshlrev_b64 v[2:3], 11, v[34:35]
	s_lshl_b32 s7, s27, 7
	v_lshlrev_b64 v[10:11], 11, v[36:37]
	v_lshlrev_b64 v[18:19], 11, v[38:39]
	v_lshlrev_b64 v[26:27], 11, v[40:41]
	v_and_b32_e32 v42, 56, v0
	v_lshl_add_u64 v[2:3], s[4:5], 0, v[2:3]
	s_and_b32 s66, s7, 0x180
	v_lshl_add_u64 v[10:11], s[4:5], 0, v[10:11]
	v_lshl_add_u64 v[18:19], s[4:5], 0, v[18:19]
	v_lshl_add_u64 v[26:27], s[4:5], 0, v[26:27]
	v_lshlrev_b32_e32 v0, 1, v42
	v_lshl_add_u64 v[2:3], v[2:3], 0, s[66:67]
	v_lshl_add_u64 v[10:11], v[10:11], 0, s[66:67]
	v_lshl_add_u64 v[18:19], v[18:19], 0, s[66:67]
	v_lshl_add_u64 v[26:27], v[26:27], 0, s[66:67]
	v_lshl_add_u64 v[6:7], v[2:3], 0, v[0:1]
	v_lshl_add_u64 v[14:15], v[10:11], 0, v[0:1]
	v_lshl_add_u64 v[22:23], v[18:19], 0, v[0:1]
	v_lshl_add_u64 v[30:31], v[26:27], 0, v[0:1]
	global_load_dwordx4 v[2:5], v[6:7], off
	s_nop 0
	global_load_dwordx4 v[6:9], v[6:7], off offset:512
	s_nop 0
	global_load_dwordx4 v[10:13], v[14:15], off
	s_nop 0
	global_load_dwordx4 v[14:17], v[14:15], off offset:512
	s_nop 0
	global_load_dwordx4 v[18:21], v[22:23], off
	s_nop 0
	global_load_dwordx4 v[22:25], v[22:23], off offset:512
	s_nop 0
	global_load_dwordx4 v[26:29], v[30:31], off
	s_nop 0
	global_load_dwordx4 v[30:33], v[30:31], off offset:512
	s_movk_i32 s7, 0x90
	v_mul_u32_u24_e32 v41, 0x210, v42
	v_mad_u64_u32 v[42:43], s[4:5], v34, s7, v[0:1]
	v_lshl_add_u32 v43, v34, 1, v41
	v_mad_u64_u32 v[34:35], s[4:5], v36, s7, v[0:1]
	v_lshl_add_u32 v35, v36, 1, v41
	v_mad_u64_u32 v[36:37], s[4:5], v38, s7, v[0:1]
	v_lshl_add_u32 v37, v38, 1, v41
	v_mad_u64_u32 v[38:39], s[4:5], v40, s7, v[0:1]
	v_lshl_add_u32 v0, v40, 1, v41
	v_and_b32_e32 v60, 15, v44
	v_bfe_u32 v61, v44, 4, 2
	s_mov_b64 s[4:5], 0xe1a6600
	s_waitcnt vmcnt(7)
	ds_write_b128 v42, v[2:5]
	s_waitcnt vmcnt(6)
	ds_write_b16 v43, v6 offset:36864
	ds_write_b16_d16_hi v43, v6 offset:37392
	ds_write_b16 v43, v7 offset:37920
	ds_write_b16_d16_hi v43, v7 offset:38448
	ds_write_b16 v43, v8 offset:38976
	ds_write_b16_d16_hi v43, v8 offset:39504
	ds_write_b16 v43, v9 offset:40032
	ds_write_b16_d16_hi v43, v9 offset:40560
	s_waitcnt vmcnt(5)
	ds_write_b128 v34, v[10:13]
	s_waitcnt vmcnt(4)
	ds_write_b16 v35, v14 offset:36864
	ds_write_b16_d16_hi v35, v14 offset:37392
	ds_write_b16 v35, v15 offset:37920
	ds_write_b16_d16_hi v35, v15 offset:38448
	ds_write_b16 v35, v16 offset:38976
	ds_write_b16_d16_hi v35, v16 offset:39504
	ds_write_b16 v35, v17 offset:40032
	ds_write_b16_d16_hi v35, v17 offset:40560
	s_waitcnt vmcnt(3)
	ds_write_b128 v36, v[18:21]
	s_waitcnt vmcnt(2)
	ds_write_b16 v37, v22 offset:36864
	ds_write_b16_d16_hi v37, v22 offset:37392
	ds_write_b16 v37, v23 offset:37920
	ds_write_b16_d16_hi v37, v23 offset:38448
	ds_write_b16 v37, v24 offset:38976
	ds_write_b16_d16_hi v37, v24 offset:39504
	ds_write_b16 v37, v25 offset:40032
	ds_write_b16_d16_hi v37, v25 offset:40560
	s_waitcnt vmcnt(1)
	ds_write_b128 v38, v[26:29]
	s_waitcnt vmcnt(0)
	ds_write_b16 v0, v30 offset:36864
	ds_write_b16_d16_hi v0, v30 offset:37392
	ds_write_b16 v0, v31 offset:37920
	ds_write_b16_d16_hi v0, v31 offset:38448
	ds_write_b16 v0, v32 offset:38976
	ds_write_b16_d16_hi v0, v32 offset:39504
	ds_write_b16 v0, v33 offset:40032
	ds_write_b16_d16_hi v0, v33 offset:40560
	v_ashrrev_i32_e32 v0, 2, v44
	v_and_b32_e32 v0, -16, v0
	v_add_u32_e32 v0, s6, v0
	v_or_b32_e32 v2, v0, v60
	v_ashrrev_i32_e32 v3, 31, v2
	v_lshlrev_b64 v[2:3], 11, v[2:3]
	v_lshl_add_u64 v[2:3], s[14:15], 0, v[2:3]
	v_lshl_add_u64 v[2:3], v[2:3], 0, s[66:67]
	v_lshl_add_u64 v[54:55], v[2:3], 0, s[4:5]
	v_lshlrev_b32_e32 v0, 4, v61
	v_lshl_add_u64 v[34:35], v[54:55], 0, v[0:1]
	s_waitcnt lgkmcnt(0)
	s_barrier
; __device__ void attn_item(const Params& p, int layer, int item, int dry) {
;     ...
;   const int t = tok0 + wid * 16 + r;
;   bf16_t* qp = cat + (size_t)t * 1024 + 768 + h * 64;
;   bf16x8 qf[2];
;   qf[0] = *(const bf16x8*)(qp + quad * 8);
;   qf[1] = *(const bf16x8*)(qp + 32 + quad * 8);
;   f32x4 s[16];
;   for (int mt = 0; mt < 16; ++mt) {
;     s[mt] = f32x4{0.f, 0.f, 0.f, 0.f};
;     for (int ks = 0; ks < 2; ++ks) {
;       bf16x8 a = *(const bf16x8*)(Ks + (mt * 16 + r) * 72 + ks * 32 + quad * 8);
;       s[mt] = __builtin_amdgcn_mfma_f32_16x16x32_bf16(a, qf[ks], s[mt], 0, 0, 0);
;     }
;   }
;   float mx = -1e30f;
;   for (int mt = 0; mt < 16; ++mt)
;     for (int j = 0; j < 4; ++j) mx = fmaxf(mx, s[mt][j]);
;   mx = fmaxf(mx, __shfl_xor(mx, 16));
;   mx = fmaxf(mx, __shfl_xor(mx, 32));
	global_load_dwordx4 v[2:5], v[34:35], off
	global_load_dwordx4 v[56:59], v[34:35], off offset:64
	v_mad_u32_u24 v98, v60, s7, v0
	ds_read_b128 v[38:41], v98 offset:18432
	ds_read_b128 v[6:9], v98
	ds_read_b128 v[10:13], v98 offset:2304
	ds_read_b128 v[14:17], v98 offset:4608
	ds_read_b128 v[18:21], v98 offset:6912
	ds_read_b128 v[22:25], v98 offset:9216
	ds_read_b128 v[26:29], v98 offset:11520
	ds_read_b128 v[30:33], v98 offset:13824
	ds_read_b128 v[34:37], v98 offset:16128
	s_mov_b32 s4, 0xf149f2ca
	s_waitcnt vmcnt(1) lgkmcnt(8)
	v_mfma_f32_16x16x32_bf16 v[62:65], v[38:41], v[2:5], 0
	ds_read_b128 v[38:41], v98 offset:20736
	s_waitcnt lgkmcnt(0)
	v_mfma_f32_16x16x32_bf16 v[66:69], v[38:41], v[2:5], 0
	ds_read_b128 v[38:41], v98 offset:23040
	s_waitcnt lgkmcnt(0)
	v_mfma_f32_16x16x32_bf16 v[70:73], v[38:41], v[2:5], 0
	ds_read_b128 v[38:41], v98 offset:25344
	s_waitcnt lgkmcnt(0)
	v_mfma_f32_16x16x32_bf16 v[74:77], v[38:41], v[2:5], 0
	ds_read_b128 v[38:41], v98 offset:27648
	s_waitcnt lgkmcnt(0)
	v_mfma_f32_16x16x32_bf16 v[78:81], v[38:41], v[2:5], 0
	ds_read_b128 v[38:41], v98 offset:29952
	s_waitcnt lgkmcnt(0)
	v_mfma_f32_16x16x32_bf16 v[82:85], v[38:41], v[2:5], 0
	ds_read_b128 v[38:41], v98 offset:64
	v_mfma_f32_16x16x32_bf16 v[6:9], v[6:9], v[2:5], 0
	s_waitcnt vmcnt(0) lgkmcnt(0)
	v_mfma_f32_16x16x32_bf16 v[86:89], v[38:41], v[56:59], v[6:9]
	s_nop 5
	ds_read_b128 v[6:9], v98 offset:2368
	v_mfma_f32_16x16x32_bf16 v[10:13], v[10:13], v[2:5], 0
	s_waitcnt lgkmcnt(0)
	v_mfma_f32_16x16x32_bf16 v[90:93], v[6:9], v[56:59], v[10:13]
	ds_read_b128 v[6:9], v98 offset:4672
	v_mfma_f32_16x16x32_bf16 v[14:17], v[14:17], v[2:5], 0
	s_waitcnt lgkmcnt(0)
	v_mfma_f32_16x16x32_bf16 v[94:97], v[6:9], v[56:59], v[14:17]
	ds_read_b128 v[6:9], v98 offset:6976
	v_mfma_f32_16x16x32_bf16 v[18:21], v[18:21], v[2:5], 0
	s_waitcnt lgkmcnt(0)
	v_mfma_f32_16x16x32_bf16 v[50:53], v[6:9], v[56:59], v[18:21]
	ds_read_b128 v[6:9], v98 offset:9280
	v_mfma_f32_16x16x32_bf16 v[22:25], v[22:25], v[2:5], 0
	s_waitcnt lgkmcnt(0)
	v_mfma_f32_16x16x32_bf16 v[46:49], v[6:9], v[56:59], v[22:25]
	ds_read_b128 v[6:9], v98 offset:11584
	v_mfma_f32_16x16x32_bf16 v[26:29], v[26:29], v[2:5], 0
	s_waitcnt lgkmcnt(0)
	v_mfma_f32_16x16x32_bf16 v[42:45], v[6:9], v[56:59], v[26:29]
	ds_read_b128 v[6:9], v98 offset:13888
	v_mfma_f32_16x16x32_bf16 v[30:33], v[30:33], v[2:5], 0
	s_waitcnt lgkmcnt(0)
	v_mfma_f32_16x16x32_bf16 v[38:41], v[6:9], v[56:59], v[30:33]
	ds_read_b128 v[6:9], v98 offset:16192
	v_mfma_f32_16x16x32_bf16 v[34:37], v[34:37], v[2:5], 0
	s_waitcnt lgkmcnt(0)
	v_mfma_f32_16x16x32_bf16 v[34:37], v[6:9], v[56:59], v[34:37]
	ds_read_b128 v[6:9], v98 offset:18496
	s_waitcnt lgkmcnt(0)
	v_mfma_f32_16x16x32_bf16 v[30:33], v[6:9], v[56:59], v[62:65]
	ds_read_b128 v[6:9], v98 offset:20800
	s_nop 1
	ds_read_b128 v[62:65], v98 offset:32320
	s_waitcnt lgkmcnt(1)
	v_mfma_f32_16x16x32_bf16 v[26:29], v[6:9], v[56:59], v[66:69]
	ds_read_b128 v[6:9], v98 offset:23104
	s_waitcnt lgkmcnt(0)
	v_mfma_f32_16x16x32_bf16 v[22:25], v[6:9], v[56:59], v[70:73]
	ds_read_b128 v[6:9], v98 offset:25408
	s_waitcnt lgkmcnt(0)
	v_mfma_f32_16x16x32_bf16 v[18:21], v[6:9], v[56:59], v[74:77]
	ds_read_b128 v[6:9], v98 offset:27712
	s_waitcnt lgkmcnt(0)
	v_mfma_f32_16x16x32_bf16 v[14:17], v[6:9], v[56:59], v[78:81]
	ds_read_b128 v[6:9], v98 offset:30016
	s_waitcnt lgkmcnt(0)
	v_mfma_f32_16x16x32_bf16 v[10:13], v[6:9], v[56:59], v[82:85]
	ds_read_b128 v[6:9], v98 offset:32256
	s_waitcnt lgkmcnt(0)
	v_mfma_f32_16x16x32_bf16 v[6:9], v[6:9], v[2:5], 0
	v_mfma_f32_16x16x32_bf16 v[6:9], v[62:65], v[56:59], v[6:9]
	ds_read_b128 v[62:65], v98 offset:34560
	s_waitcnt lgkmcnt(0)
	v_mfma_f32_16x16x32_bf16 v[2:5], v[62:65], v[2:5], 0
	ds_read_b128 v[62:65], v98 offset:34624
	s_waitcnt lgkmcnt(0)
	v_mfma_f32_16x16x32_bf16 v[2:5], v[62:65], v[56:59], v[2:5]
	v_max3_f32 v56, v86, s4, v87
	v_max3_f32 v56, v56, v88, v89
	v_max3_f32 v56, v56, v90, v91
	v_max3_f32 v56, v56, v92, v93
	v_max3_f32 v56, v56, v94, v95
	v_max3_f32 v56, v56, v96, v97
	v_max3_f32 v56, v56, v50, v51
	v_max3_f32 v56, v56, v52, v53
	v_max3_f32 v56, v56, v46, v47
	v_max3_f32 v56, v56, v48, v49
	v_max3_f32 v56, v56, v42, v43
	v_max3_f32 v56, v56, v44, v45
	v_max3_f32 v56, v56, v38, v39
	v_max3_f32 v56, v56, v40, v41
	v_max3_f32 v56, v56, v34, v35
	v_max3_f32 v56, v56, v36, v37
	v_max3_f32 v56, v56, v30, v31
	v_max3_f32 v56, v56, v32, v33
	v_max3_f32 v56, v56, v26, v27
	v_max3_f32 v56, v56, v28, v29
	v_max3_f32 v56, v56, v22, v23
	v_max3_f32 v56, v56, v24, v25
	v_max3_f32 v56, v56, v18, v19
	v_max3_f32 v56, v56, v20, v21
	v_max3_f32 v56, v56, v14, v15
	v_max3_f32 v56, v56, v16, v17
	v_max3_f32 v56, v56, v10, v11
	v_max3_f32 v56, v56, v12, v13
	v_and_b32_e32 v58, 64, v228
	v_max3_f32 v56, v56, v6, v7
	v_xor_b32_e32 v57, 16, v228
	v_add_u32_e32 v59, 64, v58
	v_max3_f32 v56, v56, v8, v9
	v_cmp_lt_i32_e32 vcc, v57, v59
	v_max3_f32 v56, v56, v2, v3
	v_max3_f32 v56, v56, v4, v5
	v_cndmask_b32_e32 v57, v228, v57, vcc
	v_lshlrev_b32_e32 v58, 2, v57
	ds_bpermute_b32 v57, v58, v56
	s_movk_i32 s4, 0x210
	s_waitcnt lgkmcnt(0)
	v_max_f32_e32 v57, v57, v57
	v_max_f32_e32 v62, v56, v57
	v_xor_b32_e32 v56, 32, v228
	v_cmp_lt_i32_e32 vcc, v56, v59
	s_nop 1
	v_cndmask_b32_e32 v56, v228, v56, vcc
	v_lshlrev_b32_e32 v57, 2, v56
	ds_bpermute_b32 v59, v57, v62
	v_lshlrev_b32_e32 v56, 3, v61
	v_sub_u32_e32 v0, v0, v56
	s_andn2_b64 vcc, exec, s[24:25]
	s_waitcnt lgkmcnt(0)
; __device__ void attn_item(const Params& p, int layer, int item, int dry) {
;     ...
;   float sum = 0.f;
;   for (int mt = 0; mt < 16; ++mt)
;     for (int j = 0; j < 4; ++j) {
;       float e = __expf((s[mt][j] - mx) * 0.125f);
;       s[mt][j] = e;
;       sum += e;
;     }
	v_max_f32_e32 v59, v59, v59
	v_max_f32_e32 v59, v62, v59
	v_sub_f32_e32 v61, v86, v59
	v_mul_f32_e32 v61, 0x3e000000, v61
	v_mul_f32_e32 v61, 0x3fb8aa3b, v61
	v_exp_f32_e32 v65, v61
	v_sub_f32_e32 v61, v87, v59
	v_mul_f32_e32 v61, 0x3e000000, v61
	v_sub_f32_e32 v62, v90, v59
	v_mul_f32_e32 v61, 0x3fb8aa3b, v61
	v_mul_f32_e32 v62, 0x3e000000, v62
	v_exp_f32_e32 v66, v61
	v_sub_f32_e32 v61, v88, v59
	v_mul_f32_e32 v62, 0x3fb8aa3b, v62
	v_mul_f32_e32 v61, 0x3e000000, v61
	v_exp_f32_e32 v68, v62
	v_sub_f32_e32 v62, v91, v59
	v_mul_f32_e32 v61, 0x3fb8aa3b, v61
	v_mul_f32_e32 v62, 0x3e000000, v62
	v_exp_f32_e32 v67, v61
	v_sub_f32_e32 v61, v89, v59
	v_mul_f32_e32 v62, 0x3fb8aa3b, v62
	v_mul_f32_e32 v61, 0x3e000000, v61
	v_exp_f32_e32 v75, v62
	v_sub_f32_e32 v62, v92, v59
	v_mul_f32_e32 v61, 0x3fb8aa3b, v61
	v_mul_f32_e32 v62, 0x3e000000, v62
	v_exp_f32_e32 v74, v61
	v_mul_f32_e32 v62, 0x3fb8aa3b, v62
	v_add_f32_e32 v61, 0, v65
	v_exp_f32_e32 v69, v62
	v_sub_f32_e32 v62, v93, v59
	v_add_f32_e32 v61, v66, v61
	v_mul_f32_e32 v62, 0x3e000000, v62
	v_add_f32_e32 v61, v67, v61
	v_mul_f32_e32 v62, 0x3fb8aa3b, v62
	v_add_f32_e32 v61, v74, v61
	v_exp_f32_e32 v70, v62
	v_add_f32_e32 v61, v68, v61
	v_add_f32_e32 v61, v75, v61
	v_sub_f32_e32 v50, v50, v59
	v_add_f32_e32 v61, v69, v61
	v_mul_f32_e32 v50, 0x3e000000, v50
	v_add_f32_e32 v71, v70, v61
	v_sub_f32_e32 v61, v94, v59
	v_mul_f32_e32 v50, 0x3fb8aa3b, v50
	v_mul_f32_e32 v61, 0x3e000000, v61
	v_sub_f32_e32 v62, v95, v59
	v_exp_f32_e32 v90, v50
	v_sub_f32_e32 v50, v51, v59
	v_mul_f32_e32 v61, 0x3fb8aa3b, v61
	v_mul_f32_e32 v62, 0x3e000000, v62
	v_sub_f32_e32 v63, v96, v59
	v_mul_f32_e32 v50, 0x3e000000, v50
	v_exp_f32_e32 v61, v61
	v_mul_f32_e32 v62, 0x3fb8aa3b, v62
	v_mul_f32_e32 v63, 0x3e000000, v63
	v_sub_f32_e32 v64, v97, v59
	v_mul_f32_e32 v50, 0x3fb8aa3b, v50
	v_exp_f32_e32 v62, v62
	v_mul_f32_e32 v63, 0x3fb8aa3b, v63
	v_mul_f32_e32 v64, 0x3e000000, v64
	v_exp_f32_e32 v91, v50
	v_sub_f32_e32 v50, v52, v59
	v_exp_f32_e32 v63, v63
	v_mul_f32_e32 v64, 0x3fb8aa3b, v64
	v_mul_f32_e32 v50, 0x3e000000, v50
	v_exp_f32_e32 v64, v64
	v_mul_f32_e32 v50, 0x3fb8aa3b, v50
	v_add_f32_e32 v71, v61, v71
	v_exp_f32_e32 v92, v50
	v_sub_f32_e32 v50, v53, v59
	v_add_f32_e32 v71, v62, v71
	v_mul_f32_e32 v50, 0x3e000000, v50
	v_sub_f32_e32 v46, v46, v59
	v_add_f32_e32 v71, v63, v71
	v_mul_f32_e32 v50, 0x3fb8aa3b, v50
	v_mul_f32_e32 v46, 0x3e000000, v46
	v_sub_f32_e32 v47, v47, v59
	v_add_f32_e32 v71, v64, v71
	v_exp_f32_e32 v53, v50
	v_mul_f32_e32 v46, 0x3fb8aa3b, v46
	v_mul_f32_e32 v47, 0x3e000000, v47
	v_sub_f32_e32 v48, v48, v59
	v_add_f32_e32 v50, v90, v71
	v_exp_f32_e32 v46, v46
	v_mul_f32_e32 v47, 0x3fb8aa3b, v47
	v_mul_f32_e32 v48, 0x3e000000, v48
	v_sub_f32_e32 v49, v49, v59
	v_add_f32_e32 v50, v91, v50
	v_exp_f32_e32 v47, v47
	v_mul_f32_e32 v48, 0x3fb8aa3b, v48
	v_mul_f32_e32 v49, 0x3e000000, v49
	v_add_f32_e32 v50, v92, v50
	v_exp_f32_e32 v48, v48
	v_mul_f32_e32 v49, 0x3fb8aa3b, v49
	v_add_f32_e32 v50, v53, v50
	v_exp_f32_e32 v49, v49
	v_add_f32_e32 v50, v46, v50
	v_sub_f32_e32 v42, v42, v59
	v_add_f32_e32 v50, v47, v50
	v_mul_f32_e32 v42, 0x3e000000, v42
	v_add_f32_e32 v50, v48, v50
	v_mul_f32_e32 v42, 0x3fb8aa3b, v42
	v_add_f32_e32 v71, v49, v50
	v_exp_f32_e32 v50, v42
	v_sub_f32_e32 v42, v43, v59
	v_mul_f32_e32 v42, 0x3e000000, v42
	v_mul_f32_e32 v42, 0x3fb8aa3b, v42
	v_exp_f32_e32 v51, v42
	v_sub_f32_e32 v42, v44, v59
	v_mul_f32_e32 v42, 0x3e000000, v42
	v_mul_f32_e32 v42, 0x3fb8aa3b, v42
	v_exp_f32_e32 v52, v42
	v_sub_f32_e32 v42, v45, v59
	v_mul_f32_e32 v42, 0x3e000000, v42
	v_sub_f32_e32 v38, v38, v59
	v_mul_f32_e32 v42, 0x3fb8aa3b, v42
	v_mul_f32_e32 v38, 0x3e000000, v38
	v_sub_f32_e32 v39, v39, v59
	v_exp_f32_e32 v45, v42
	v_mul_f32_e32 v38, 0x3fb8aa3b, v38
	v_mul_f32_e32 v39, 0x3e000000, v39
	v_sub_f32_e32 v40, v40, v59
	v_add_f32_e32 v42, v50, v71
	v_exp_f32_e32 v38, v38
	v_mul_f32_e32 v39, 0x3fb8aa3b, v39
	v_mul_f32_e32 v40, 0x3e000000, v40
	v_sub_f32_e32 v41, v41, v59
	v_add_f32_e32 v42, v51, v42
	v_exp_f32_e32 v39, v39
	v_mul_f32_e32 v40, 0x3fb8aa3b, v40
	v_mul_f32_e32 v41, 0x3e000000, v41
	v_add_f32_e32 v42, v52, v42
	v_exp_f32_e32 v40, v40
	v_mul_f32_e32 v41, 0x3fb8aa3b, v41
	v_add_f32_e32 v42, v45, v42
	v_exp_f32_e32 v41, v41
	v_add_f32_e32 v42, v38, v42
	v_sub_f32_e32 v34, v34, v59
	v_add_f32_e32 v42, v39, v42
	v_mul_f32_e32 v34, 0x3e000000, v34
	v_add_f32_e32 v42, v40, v42
	v_mul_f32_e32 v34, 0x3fb8aa3b, v34
	v_add_f32_e32 v71, v41, v42
	v_exp_f32_e32 v42, v34
	v_sub_f32_e32 v34, v35, v59
	v_mul_f32_e32 v34, 0x3e000000, v34
	v_mul_f32_e32 v34, 0x3fb8aa3b, v34
	v_exp_f32_e32 v43, v34
	v_sub_f32_e32 v34, v36, v59
	v_mul_f32_e32 v34, 0x3e000000, v34
	v_mul_f32_e32 v34, 0x3fb8aa3b, v34
	v_exp_f32_e32 v44, v34
	v_sub_f32_e32 v34, v37, v59
	v_mul_f32_e32 v34, 0x3e000000, v34
	v_sub_f32_e32 v30, v30, v59
	v_mul_f32_e32 v34, 0x3fb8aa3b, v34
	v_mul_f32_e32 v30, 0x3e000000, v30
	v_sub_f32_e32 v31, v31, v59
	v_exp_f32_e32 v37, v34
	v_mul_f32_e32 v30, 0x3fb8aa3b, v30
	v_mul_f32_e32 v31, 0x3e000000, v31
	v_sub_f32_e32 v32, v32, v59
	v_add_f32_e32 v34, v42, v71
	v_exp_f32_e32 v30, v30
	v_mul_f32_e32 v31, 0x3fb8aa3b, v31
	v_mul_f32_e32 v32, 0x3e000000, v32
	v_sub_f32_e32 v33, v33, v59
	v_add_f32_e32 v34, v43, v34
	v_exp_f32_e32 v31, v31
	v_mul_f32_e32 v32, 0x3fb8aa3b, v32
	v_mul_f32_e32 v33, 0x3e000000, v33
	v_add_f32_e32 v34, v44, v34
	v_exp_f32_e32 v32, v32
	v_mul_f32_e32 v33, 0x3fb8aa3b, v33
	v_add_f32_e32 v34, v37, v34
	v_exp_f32_e32 v33, v33
	v_add_f32_e32 v34, v30, v34
	v_sub_f32_e32 v26, v26, v59
	v_add_f32_e32 v34, v31, v34
	v_mul_f32_e32 v26, 0x3e000000, v26
	v_add_f32_e32 v34, v32, v34
; __device__ __forceinline__ unsigned short f2bf(float f) { return (unsigned short)(pack2(f, 0.f) & 0xffffu); }
; __device__ void attn_item(const Params& p, int layer, int item, int dry) {
;     ...
;   float sum = 0.f;
;   for (int mt = 0; mt < 16; ++mt)
;     for (int j = 0; j < 4; ++j) {
;       float e = __expf((s[mt][j] - mx) * 0.125f);
;       s[mt][j] = e;
;       sum += e;
;     }
;   sum += __shfl_xor(sum, 16);
;   sum += __shfl_xor(sum, 32);
;   const float inv = 1.f / sum;
;   f32x4 o[4] = {};
;   for (int ks = 0; ks < 8; ++ks) {
;     bf16x8 pb;
;     for (int j = 0; j < 4; ++j) {
;       pb[j] = (short)f2bf(s[2 * ks][j]);
;       pb[4 + j] = (short)f2bf(s[2 * ks + 1][j]);
;     }
;     for (int dt = 0; dt < 4; ++dt) {
;       const bf16_t* vp = Vt + (dt * 16 + r) * 264 + ks * 32 + quad * 4;
;       uint2 v0 = *(const uint2*)vp, v1 = *(const uint2*)(vp + 16);
;       bf16x8 av;
;       av[0] = (short)(v0.x & 0xffff); av[1] = (short)(v0.x >> 16); av[2] = (short)(v0.y & 0xffff); av[3] = (short)(v0.y >> 16);
;       av[4] = (short)(v1.x & 0xffff); av[5] = (short)(v1.x >> 16); av[6] = (short)(v1.y & 0xffff); av[7] = (short)(v1.y >> 16);
;       o[dt] = __builtin_amdgcn_mfma_f32_16x16x32_bf16(av, pb, o[dt], 0, 0, 0);
	v_mul_f32_e32 v26, 0x3fb8aa3b, v26
	v_add_f32_e32 v71, v33, v34
	v_exp_f32_e32 v34, v26
	v_sub_f32_e32 v26, v27, v59
	v_mul_f32_e32 v26, 0x3e000000, v26
	v_mul_f32_e32 v26, 0x3fb8aa3b, v26
	v_exp_f32_e32 v35, v26
	v_sub_f32_e32 v26, v28, v59
	v_mul_f32_e32 v26, 0x3e000000, v26
	v_mul_f32_e32 v26, 0x3fb8aa3b, v26
	v_exp_f32_e32 v28, v26
	v_sub_f32_e32 v26, v29, v59
	v_mul_f32_e32 v26, 0x3e000000, v26
	v_sub_f32_e32 v22, v22, v59
	v_mul_f32_e32 v26, 0x3fb8aa3b, v26
	v_mul_f32_e32 v22, 0x3e000000, v22
	v_sub_f32_e32 v23, v23, v59
	v_exp_f32_e32 v36, v26
	v_mul_f32_e32 v22, 0x3fb8aa3b, v22
	v_mul_f32_e32 v23, 0x3e000000, v23
	v_sub_f32_e32 v24, v24, v59
	v_add_f32_e32 v26, v34, v71
	v_exp_f32_e32 v22, v22
	v_mul_f32_e32 v23, 0x3fb8aa3b, v23
	v_mul_f32_e32 v24, 0x3e000000, v24
	v_sub_f32_e32 v25, v25, v59
	v_add_f32_e32 v26, v35, v26
	v_exp_f32_e32 v23, v23
	v_mul_f32_e32 v24, 0x3fb8aa3b, v24
	v_mul_f32_e32 v25, 0x3e000000, v25
	v_add_f32_e32 v26, v28, v26
	v_exp_f32_e32 v24, v24
	v_mul_f32_e32 v25, 0x3fb8aa3b, v25
	v_add_f32_e32 v26, v36, v26
	v_exp_f32_e32 v25, v25
	v_add_f32_e32 v26, v22, v26
	v_sub_f32_e32 v18, v18, v59
	v_sub_f32_e32 v20, v20, v59
	v_add_f32_e32 v26, v23, v26
	v_mul_f32_e32 v18, 0x3e000000, v18
	v_sub_f32_e32 v19, v19, v59
	v_mul_f32_e32 v20, 0x3e000000, v20
	v_add_f32_e32 v26, v24, v26
	v_mul_f32_e32 v18, 0x3fb8aa3b, v18
	v_mul_f32_e32 v19, 0x3e000000, v19
	v_mul_f32_e32 v20, 0x3fb8aa3b, v20
	v_add_f32_e32 v29, v25, v26
	v_exp_f32_e32 v18, v18
	v_mul_f32_e32 v19, 0x3fb8aa3b, v19
	v_exp_f32_e32 v26, v20
	v_sub_f32_e32 v20, v21, v59
	v_exp_f32_e32 v19, v19
	v_mul_f32_e32 v20, 0x3e000000, v20
	v_sub_f32_e32 v14, v14, v59
	v_mul_f32_e32 v20, 0x3fb8aa3b, v20
	v_mul_f32_e32 v14, 0x3e000000, v14
	v_sub_f32_e32 v15, v15, v59
	v_exp_f32_e32 v27, v20
	v_mul_f32_e32 v14, 0x3fb8aa3b, v14
	v_mul_f32_e32 v15, 0x3e000000, v15
	v_sub_f32_e32 v16, v16, v59
	v_add_f32_e32 v20, v18, v29
	v_exp_f32_e32 v14, v14
	v_mul_f32_e32 v15, 0x3fb8aa3b, v15
	v_mul_f32_e32 v16, 0x3e000000, v16
	v_sub_f32_e32 v17, v17, v59
	v_add_f32_e32 v20, v19, v20
	v_exp_f32_e32 v15, v15
	v_mul_f32_e32 v16, 0x3fb8aa3b, v16
	v_mul_f32_e32 v17, 0x3e000000, v17
	v_sub_f32_e32 v10, v10, v59
	v_add_f32_e32 v20, v26, v20
	v_exp_f32_e32 v16, v16
	v_mul_f32_e32 v17, 0x3fb8aa3b, v17
	v_mul_f32_e32 v10, 0x3e000000, v10
	v_sub_f32_e32 v11, v11, v59
	v_add_f32_e32 v20, v27, v20
	v_exp_f32_e32 v17, v17
	v_mul_f32_e32 v10, 0x3fb8aa3b, v10
	v_mul_f32_e32 v11, 0x3e000000, v11
	v_sub_f32_e32 v12, v12, v59
	v_add_f32_e32 v20, v14, v20
	v_exp_f32_e32 v10, v10
	v_mul_f32_e32 v11, 0x3fb8aa3b, v11
	v_mul_f32_e32 v12, 0x3e000000, v12
	v_sub_f32_e32 v13, v13, v59
	v_add_f32_e32 v20, v15, v20
	v_exp_f32_e32 v11, v11
	v_mul_f32_e32 v12, 0x3fb8aa3b, v12
	v_mul_f32_e32 v13, 0x3e000000, v13
	v_add_f32_e32 v20, v16, v20
	v_exp_f32_e32 v12, v12
	v_mul_f32_e32 v13, 0x3fb8aa3b, v13
	v_add_f32_e32 v20, v17, v20
	v_exp_f32_e32 v13, v13
	v_add_f32_e32 v20, v10, v20
	v_add_f32_e32 v20, v11, v20
	v_add_f32_e32 v20, v12, v20
	v_add_f32_e32 v86, v13, v20
	v_sub_f32_e32 v7, v7, v59
	v_mad_u32_u24 v20, v60, s4, v0
	v_mul_f32_e32 v29, 0x3e000000, v7
	v_add_u32_e32 v21, 0x9000, v20
	v_add_u32_e32 v7, 0xb000, v20
	v_add_u32_e32 v0, 0xd000, v20
	v_add_u32_e32 v20, 0xf000, v20
	v_cvt_pk_bf16_f32 v69, v69, v70
	ds_read2_b64 v[70:73], v21 offset1:4
	v_cvt_pk_bf16_f32 v68, v68, v75
	v_cvt_pk_bf16_f32 v67, v67, v74
	ds_read2_b64 v[74:77], v7 offset0:32 offset1:36
	ds_read2_b64 v[78:81], v0 offset0:64 offset1:68
	ds_read2_b64 v[82:85], v20 offset0:96 offset1:100
	v_sub_f32_e32 v6, v6, v59
	v_mul_f32_e32 v6, 0x3e000000, v6
	v_mul_f32_e32 v6, 0x3fb8aa3b, v6
	v_exp_f32_e32 v6, v6
	s_waitcnt lgkmcnt(3)
	v_bfi_b32 v72, s65, v72, v72
	s_waitcnt lgkmcnt(2)
	v_bfi_b32 v76, s65, v76, v76
	s_waitcnt lgkmcnt(1)
	v_bfi_b32 v80, s65, v80, v80
	v_mul_f32_e32 v29, 0x3fb8aa3b, v29
	s_waitcnt lgkmcnt(0)
	v_bfi_b32 v84, s65, v84, v84
	v_exp_f32_e32 v29, v29
	v_cvt_pk_bf16_f32 v66, v65, v66
	v_add_f32_e32 v60, v6, v86
	ds_read2_b64 v[86:89], v21 offset0:8 offset1:12
	v_mfma_f32_16x16x32_bf16 v[70:73], v[70:73], v[66:69], 0
	v_add_f32_e32 v94, v29, v60
	v_sub_f32_e32 v8, v8, v59
	v_mul_f32_e32 v8, 0x3e000000, v8
	v_mfma_f32_16x16x32_bf16 v[74:77], v[74:77], v[66:69], 0
	s_waitcnt lgkmcnt(0)
	v_bfi_b32 v88, s65, v88, v88
	v_mul_f32_e32 v8, 0x3fb8aa3b, v8
	v_sub_f32_e32 v2, v2, v59
	v_mfma_f32_16x16x32_bf16 v[78:81], v[78:81], v[66:69], 0
	v_mul_f32_e32 v2, 0x3e000000, v2
	v_mul_f32_e32 v2, 0x3fb8aa3b, v2
	v_cvt_pk_bf16_f32 v27, v26, v27
	v_mfma_f32_16x16x32_bf16 v[66:69], v[82:85], v[66:69], 0
	v_cvt_pk_bf16_f32 v83, v63, v64
	v_cvt_pk_bf16_f32 v82, v61, v62
	ds_read2_b64 v[60:63], v0 offset0:72 offset1:76
	v_cvt_pk_bf16_f32 v85, v92, v53
	v_cvt_pk_bf16_f32 v84, v90, v91
	ds_read2_b64 v[90:93], v7 offset0:40 offset1:44
	v_cvt_pk_bf16_f32 v53, v52, v45
	s_waitcnt lgkmcnt(1)
	v_bfi_b32 v62, s65, v62, v62
	v_mfma_f32_16x16x32_bf16 v[70:73], v[86:89], v[82:85], v[70:73]
	ds_read2_b64 v[86:89], v20 offset0:104 offset1:108
	v_cvt_pk_bf16_f32 v52, v50, v51
	v_cvt_pk_bf16_f32 v51, v48, v49
	v_mfma_f32_16x16x32_bf16 v[60:63], v[60:63], v[82:85], v[78:81]
	v_cvt_pk_bf16_f32 v50, v46, v47
	ds_read2_b64 v[46:49], v0 offset0:80 offset1:84
	s_waitcnt lgkmcnt(2)
	v_bfi_b32 v92, s65, v92, v92
	ds_read2_b64 v[78:81], v21 offset0:16 offset1:20
	s_waitcnt lgkmcnt(2)
	v_bfi_b32 v88, s65, v88, v88
	v_mfma_f32_16x16x32_bf16 v[74:77], v[90:93], v[82:85], v[74:77]
	s_waitcnt lgkmcnt(0)
; __device__ __forceinline__ unsigned short f2bf(float f) { return (unsigned short)(pack2(f, 0.f) & 0xffffu); }
; __device__ void attn_item(const Params& p, int layer, int item, int dry) {
;     ...
;   sum += __shfl_xor(sum, 16);
;   sum += __shfl_xor(sum, 32);
;   const float inv = 1.f / sum;
;   f32x4 o[4] = {};
;   for (int ks = 0; ks < 8; ++ks) {
;     bf16x8 pb;
;     for (int j = 0; j < 4; ++j) {
;       pb[j] = (short)f2bf(s[2 * ks][j]);
;       pb[4 + j] = (short)f2bf(s[2 * ks + 1][j]);
;     }
;     for (int dt = 0; dt < 4; ++dt) {
;       const bf16_t* vp = Vt + (dt * 16 + r) * 264 + ks * 32 + quad * 4;
;       uint2 v0 = *(const uint2*)vp, v1 = *(const uint2*)(vp + 16);
;       bf16x8 av;
;       av[0] = (short)(v0.x & 0xffff); av[1] = (short)(v0.x >> 16); av[2] = (short)(v0.y & 0xffff); av[3] = (short)(v0.y >> 16);
;       av[4] = (short)(v1.x & 0xffff); av[5] = (short)(v1.x >> 16); av[6] = (short)(v1.y & 0xffff); av[7] = (short)(v1.y >> 16);
;       o[dt] = __builtin_amdgcn_mfma_f32_16x16x32_bf16(av, pb, o[dt], 0, 0, 0);
;     }
;   }
;   for (int dt = 0; dt < 4; ++dt) {
;     uint2 ov;
;     ov.x = pack2(o[dt][0] * inv, o[dt][1] * inv);
;     ov.y = pack2(o[dt][2] * inv, o[dt][3] * inv);
;     if (!dry) *(uint2*)(qp + dt * 16 + quad * 4) = ov;
;   }
	v_bfi_b32 v80, s65, v80, v80
	v_bfi_b32 v48, s65, v48, v48
	v_cvt_pk_bf16_f32 v45, v44, v37
	v_mfma_f32_16x16x32_bf16 v[64:67], v[86:89], v[82:85], v[66:69]
	ds_read2_b64 v[82:85], v7 offset0:48 offset1:52
	v_cvt_pk_bf16_f32 v44, v42, v43
	v_cvt_pk_bf16_f32 v43, v40, v41
	v_mfma_f32_16x16x32_bf16 v[68:71], v[78:81], v[50:53], v[70:73]
	ds_read2_b64 v[78:81], v20 offset0:112 offset1:116
	v_cvt_pk_bf16_f32 v42, v38, v39
	ds_read2_b64 v[38:41], v0 offset0:88 offset1:92
	v_mfma_f32_16x16x32_bf16 v[46:49], v[46:49], v[50:53], v[60:63]
	s_waitcnt lgkmcnt(2)
	v_bfi_b32 v84, s65, v84, v84
	s_waitcnt lgkmcnt(1)
	v_bfi_b32 v80, s65, v80, v80
	v_cvt_pk_bf16_f32 v37, v28, v36
	ds_read2_b64 v[60:63], v21 offset0:24 offset1:28
	s_waitcnt lgkmcnt(1)
	v_bfi_b32 v40, s65, v40, v40
	v_mfma_f32_16x16x32_bf16 v[72:75], v[82:85], v[50:53], v[74:77]
	v_cvt_pk_bf16_f32 v36, v34, v35
	v_cvt_pk_bf16_f32 v35, v32, v33
	s_waitcnt lgkmcnt(0)
	v_bfi_b32 v62, s65, v62, v62
	v_mfma_f32_16x16x32_bf16 v[50:53], v[78:81], v[50:53], v[64:67]
	v_cvt_pk_bf16_f32 v34, v30, v31
	ds_read2_b64 v[30:33], v0 offset0:96 offset1:100
	v_exp_f32_e32 v90, v8
	ds_read2_b64 v[64:67], v7 offset0:56 offset1:60
	v_mfma_f32_16x16x32_bf16 v[60:63], v[60:63], v[42:45], v[68:71]
	v_sub_f32_e32 v8, v9, v59
	s_waitcnt lgkmcnt(1)
	v_bfi_b32 v32, s65, v32, v32
	v_mul_f32_e32 v8, 0x3e000000, v8
	ds_read2_b64 v[68:71], v20 offset0:120 offset1:124
	v_mfma_f32_16x16x32_bf16 v[38:41], v[38:41], v[42:45], v[46:49]
	s_waitcnt lgkmcnt(1)
	v_bfi_b32 v66, s65, v66, v66
	v_mul_f32_e32 v8, 0x3fb8aa3b, v8
	v_exp_f32_e32 v9, v2
	ds_read2_b64 v[46:49], v21 offset0:32 offset1:36
	s_waitcnt lgkmcnt(1)
	v_bfi_b32 v70, s65, v70, v70
	v_mfma_f32_16x16x32_bf16 v[64:67], v[64:67], v[42:45], v[72:75]
	v_sub_f32_e32 v2, v3, v59
	v_exp_f32_e32 v76, v8
	s_waitcnt lgkmcnt(0)
	v_bfi_b32 v48, s65, v48, v48
	v_mfma_f32_16x16x32_bf16 v[42:45], v[68:71], v[42:45], v[50:53]
	v_mul_f32_e32 v2, 0x3e000000, v2
	v_mul_f32_e32 v2, 0x3fb8aa3b, v2
	v_exp_f32_e32 v28, v2
	ds_read2_b64 v[50:53], v7 offset0:64 offset1:68
	v_mfma_f32_16x16x32_bf16 v[46:49], v[46:49], v[34:37], v[60:63]
	v_add_f32_e32 v8, v90, v94
	v_add_f32_e32 v8, v76, v8
	v_add_f32_e32 v2, v9, v8
	ds_read2_b64 v[60:63], v20 offset0:128 offset1:132
	v_mfma_f32_16x16x32_bf16 v[30:33], v[30:33], v[34:37], v[38:41]
	s_waitcnt lgkmcnt(1)
	v_bfi_b32 v52, s65, v52, v52
	v_add_f32_e32 v8, v28, v2
	v_sub_f32_e32 v2, v4, v59
	ds_read2_b64 v[38:41], v21 offset0:40 offset1:44
	s_waitcnt lgkmcnt(1)
	v_bfi_b32 v62, s65, v62, v62
	v_mfma_f32_16x16x32_bf16 v[50:53], v[50:53], v[34:37], v[64:67]
	v_mul_f32_e32 v2, 0x3e000000, v2
	v_mul_f32_e32 v2, 0x3fb8aa3b, v2
	s_waitcnt lgkmcnt(0)
	v_bfi_b32 v40, s65, v40, v40
	v_mfma_f32_16x16x32_bf16 v[34:37], v[60:63], v[34:37], v[42:45]
	ds_read2_b64 v[60:63], v0 offset0:104 offset1:108
	v_cvt_pk_bf16_f32 v26, v18, v19
	v_cvt_pk_bf16_f32 v25, v24, v25
	v_cvt_pk_bf16_f32 v24, v22, v23
	v_exp_f32_e32 v18, v2
	v_sub_f32_e32 v19, v5, v59
	ds_read2_b64 v[2:5], v21 offset0:48 offset1:52
	ds_read2_b64 v[42:45], v7 offset0:72 offset1:76
	v_mfma_f32_16x16x32_bf16 v[38:41], v[38:41], v[24:27], v[46:49]
	v_cvt_pk_bf16_f32 v13, v12, v13
	v_cvt_pk_bf16_f32 v12, v10, v11
	v_cvt_pk_bf16_f32 v11, v16, v17
	ds_read2_b64 v[46:49], v20 offset0:136 offset1:140
	v_cvt_pk_bf16_f32 v10, v14, v15
	ds_read2_b64 v[14:17], v0 offset0:112 offset1:116
	s_waitcnt lgkmcnt(4)
	v_bfi_b32 v62, s65, v62, v62
	s_waitcnt lgkmcnt(3)
	v_bfi_b32 v4, s65, v4, v4
	s_waitcnt lgkmcnt(2)
	v_bfi_b32 v44, s65, v44, v44
	s_waitcnt lgkmcnt(1)
	v_bfi_b32 v48, s65, v48, v48
	s_waitcnt lgkmcnt(0)
	v_bfi_b32 v16, s65, v16, v16
	v_mfma_f32_16x16x32_bf16 v[30:33], v[60:63], v[24:27], v[30:33]
	v_mul_f32_e32 v19, 0x3e000000, v19
	v_mul_f32_e32 v19, 0x3fb8aa3b, v19
	v_exp_f32_e32 v19, v19
	v_mfma_f32_16x16x32_bf16 v[2:5], v[2:5], v[10:13], v[38:41]
	v_add_f32_e32 v8, v18, v8
	s_nop 1
	ds_read2_b64 v[38:41], v20 offset0:144 offset1:148
	v_mfma_f32_16x16x32_bf16 v[42:45], v[42:45], v[24:27], v[50:53]
	s_waitcnt lgkmcnt(0)
	v_bfi_b32 v40, s65, v40, v40
	v_mfma_f32_16x16x32_bf16 v[22:25], v[46:49], v[24:27], v[34:37]
	s_nop 2
	ds_read2_b64 v[34:37], v7 offset0:80 offset1:84
	v_mfma_f32_16x16x32_bf16 v[14:17], v[14:17], v[10:13], v[30:33]
	s_waitcnt lgkmcnt(0)
	v_bfi_b32 v36, s65, v36, v36
	s_nop 0
	ds_read2_b64 v[30:33], v21 offset0:56 offset1:60
	v_mfma_f32_16x16x32_bf16 v[22:25], v[38:41], v[10:13], v[22:25]
	v_cvt_pk_bf16_f32 v41, v18, v19
	v_cvt_pk_bf16_f32 v40, v9, v28
	v_cvt_pk_bf16_f32 v39, v90, v76
	s_waitcnt lgkmcnt(0)
	v_bfi_b32 v32, s65, v32, v32
	v_cvt_pk_bf16_f32 v38, v6, v29
	v_mfma_f32_16x16x32_bf16 v[34:37], v[34:37], v[10:13], v[42:45]
	v_add_f32_e32 v21, v19, v8
	ds_read2_b64 v[8:11], v7 offset0:88 offset1:92
	ds_read2_b64 v[26:29], v0 offset0:120 offset1:124
	v_mfma_f32_16x16x32_bf16 v[2:5], v[30:33], v[38:41], v[2:5]
	ds_read2_b64 v[30:33], v20 offset0:152 offset1:156
	ds_bpermute_b32 v0, v58, v21
	s_waitcnt lgkmcnt(3)
	v_bfi_b32 v10, s65, v10, v10
	s_waitcnt lgkmcnt(2)
	v_bfi_b32 v28, s65, v28, v28
	s_waitcnt lgkmcnt(1)
	v_bfi_b32 v32, s65, v32, v32
	s_waitcnt lgkmcnt(0)
	v_add_f32_e32 v0, v21, v0
	ds_bpermute_b32 v18, v57, v0
	v_mfma_f32_16x16x32_bf16 v[6:9], v[8:11], v[38:41], v[34:37]
	v_mfma_f32_16x16x32_bf16 v[10:13], v[26:29], v[38:41], v[14:17]
	v_mfma_f32_16x16x32_bf16 v[14:17], v[30:33], v[38:41], v[22:25]
	s_cbranch_vccnz .LBB0_1351
	s_waitcnt lgkmcnt(0)
	v_add_f32_e32 v0, v0, v18
	v_div_scale_f32 v18, s[4:5], v0, v0, 1.0
	v_rcp_f32_e32 v19, v18
	v_mov_b32_e32 v57, v1
	v_lshl_add_u64 v[20:21], v[54:55], 0, v[56:57]
	v_fma_f32 v22, -v18, v19, 1.0
	v_fmac_f32_e32 v19, v22, v19
	v_div_scale_f32 v22, vcc, 1.0, v0, 1.0
	v_mul_f32_e32 v23, v22, v19
	v_fma_f32 v24, -v18, v23, v22
	v_fmac_f32_e32 v23, v24, v19
	v_fma_f32 v18, -v18, v23, v22
	v_div_fmas_f32 v18, v18, v19, v23
	v_div_fixup_f32 v0, v18, v0, 1.0
	v_pk_mul_f32 v[4:5], v[0:1], v[4:5] op_sel_hi:[0,1]
	v_pk_mul_f32 v[2:3], v[0:1], v[2:3] op_sel_hi:[0,1]
	v_cvt_pk_bf16_f32 v5, v4, v5
	v_cvt_pk_bf16_f32 v4, v2, v3
	global_store_dwordx2 v[20:21], v[4:5], off
	v_pk_mul_f32 v[2:3], v[0:1], v[8:9] op_sel_hi:[0,1]
	v_pk_mul_f32 v[4:5], v[0:1], v[6:7] op_sel_hi:[0,1]
	v_cvt_pk_bf16_f32 v3, v2, v3
	v_cvt_pk_bf16_f32 v2, v4, v5
	global_store_dwordx2 v[20:21], v[2:3], off offset:32
	v_pk_mul_f32 v[2:3], v[0:1], v[12:13] op_sel_hi:[0,1]
	v_pk_mul_f32 v[4:5], v[0:1], v[10:11] op_sel_hi:[0,1]
	v_cvt_pk_bf16_f32 v3, v2, v3
	v_cvt_pk_bf16_f32 v2, v4, v5
	global_store_dwordx2 v[20:21], v[2:3], off offset:64
	v_pk_mul_f32 v[2:3], v[0:1], v[16:17] op_sel_hi:[0,1]
	v_pk_mul_f32 v[4:5], v[0:1], v[14:15] op_sel_hi:[0,1]
	v_cvt_pk_bf16_f32 v3, v2, v3
	v_cvt_pk_bf16_f32 v2, v4, v5
	global_store_dwordx2 v[20:21], v[2:3], off offset:96

; __device__ void transpose_item(const Params& p, int item) {
;     ...
;   const int cb = item % 12, tb = item / 12;
;   const int ch0 = cb * 64, t0 = tb * 128;
;   for (int i = 0; i < 2; ++i) {
;     int idx = tid + 512 * i;
;     int row = idx >> 4, c8 = (idx & 15) * 8;
;     uint4 u = *(const uint4*)(PT + (size_t)(ch0 + row) * T_TOK + t0 + c8);
;     unsigned* d = (unsigned*)(tl + row * 130 + c8);
;     d[0] = u.x; d[1] = u.y; d[2] = u.z; d[3] = u.w;
;   }
;   __syncthreads();
;   for (int i = 0; i < 2; ++i) {
;     int idx = tid + 512 * i;
;     int tok = idx >> 3, c8 = (idx & 7) * 8;
;     unsigned short v[8];
;     for (int j = 0; j < 8; ++j) v[j] = tl[(c8 + j) * 130 + tok];
;     uint4 o;
;     o.x = v[0] | ((unsigned)v[1] << 16); o.y = v[2] | ((unsigned)v[3] << 16);
;     o.z = v[4] | ((unsigned)v[5] << 16); o.w = v[6] | ((unsigned)v[7] << 16);
;     *(uint4*)(cat + (size_t)(t0 + tok) * 1024 + ch0 + c8) = o;
;   }
.LBB0_1353:
	s_mov_b64 s[4:5], -1
	s_and_b64 vcc, exec, s[2:3]
	s_cbranch_vccz .LBB0_1355
	s_mul_hi_i32 s4, s88, 0x2aaaaaab
	v_mov_b32_e32 v10, v208
	s_lshr_b32 s5, s4, 31
	s_ashr_i32 s4, s4, 1
	s_add_i32 s4, s4, s5
	s_load_dwordx4 s[28:31], s[72:73], 0xe8
	s_mul_i32 s5, s4, 12
	s_sub_i32 s5, s88, s5
	s_lshl_b32 s4, s4, 7
	s_lshl_b32 s6, s5, 6
	s_ashr_i32 s5, s4, 31
	s_lshl_b64 s[8:9], s[4:5], 1
	v_ashrrev_i32_e32 v4, 4, v10
	s_waitcnt lgkmcnt(0)
	s_add_u32 s8, s30, s8
	v_lshlrev_b32_e32 v0, 4, v10
	v_add_u32_e32 v2, s6, v4
	s_addc_u32 s9, s31, s9
	v_and_b32_e32 v0, 0xf0, v0
	v_ashrrev_i32_e32 v3, 31, v2
	v_lshl_add_u64 v[6:7], s[8:9], 0, v[0:1]
	v_lshlrev_b64 v[2:3], 17, v[2:3]
	v_lshl_add_u64 v[2:3], v[6:7], 0, v[2:3]
	s_movk_i32 s5, 0x104
	v_mad_u64_u32 v[8:9], s[8:9], v4, s5, v[0:1]
	global_load_dwordx4 v[2:5], v[2:3], off
	v_add_u32_e32 v12, 0x200, v10
	v_ashrrev_i32_e32 v176, 4, v12
	v_add_u32_e32 v178, s6, v176
	v_ashrrev_i32_e32 v179, 31, v178
	v_lshlrev_b64 v[178:179], 17, v[178:179]
	v_lshl_add_u64 v[178:179], v[6:7], 0, v[178:179]
	global_load_dwordx4 v[180:183], v[178:179], off
	s_ashr_i32 s7, s6, 31
	v_lshlrev_b32_e32 v11, 3, v10
	s_waitcnt vmcnt(1)
	ds_write2_b32 v8, v2, v3 offset1:1
	ds_write2_b32 v8, v4, v5 offset0:2 offset1:3
	v_ashrrev_i32_e32 v4, 4, v12
	v_mad_u64_u32 v[6:7], s[8:9], v4, s5, v[0:1]
	s_lshl_b64 s[6:7], s[6:7], 1
	s_add_u32 s6, s12, s6
	s_addc_u32 s7, s13, s7
	v_ashrrev_i32_e32 v8, 3, v10
	s_mov_b32 s5, 0x5040100
	s_waitcnt vmcnt(0)
	ds_write2_b32 v6, v180, v181 offset1:1
	ds_write2_b32 v6, v182, v183 offset0:2 offset1:3
	v_and_b32_e32 v2, 56, v11
	v_lshlrev_b32_e32 v0, 1, v2
	v_lshl_add_u64 v[6:7], s[6:7], 0, v[0:1]
	v_mul_u32_u24_e32 v0, 0x104, v2
	v_lshl_add_u32 v2, v8, 1, v0
	s_waitcnt lgkmcnt(0)
	s_barrier
	ds_read_u16 v9, v2
	ds_read_u16 v10, v2 offset:260
	ds_read_u16 v3, v2 offset:520
	ds_read_u16 v11, v2 offset:780
	ds_read_u16 v4, v2 offset:1040
	ds_read_u16 v13, v2 offset:1300
	ds_read_u16 v5, v2 offset:1560
	ds_read_u16 v2, v2 offset:1820
	v_add_u32_e32 v8, s4, v8
	s_waitcnt lgkmcnt(4)
	v_perm_b32 v3, v11, v3, s5
	s_waitcnt lgkmcnt(2)
	v_perm_b32 v4, v13, v4, s5
	s_waitcnt lgkmcnt(0)
	v_perm_b32 v5, v2, v5, s5
	v_perm_b32 v2, v10, v9, s5
	v_ashrrev_i32_e32 v9, 31, v8
	v_lshlrev_b64 v[8:9], 11, v[8:9]
	v_lshl_add_u64 v[8:9], v[6:7], 0, v[8:9]
	global_store_dwordx4 v[8:9], v[2:5], off
	v_ashrrev_i32_e32 v8, 3, v12
	v_lshl_add_u32 v0, v8, 1, v0
	ds_read_u16 v2, v0
	ds_read_u16 v9, v0 offset:260
	ds_read_u16 v3, v0 offset:520
	ds_read_u16 v10, v0 offset:780
	ds_read_u16 v4, v0 offset:1040
	ds_read_u16 v11, v0 offset:1300
	ds_read_u16 v5, v0 offset:1560
	ds_read_u16 v0, v0 offset:1820
	v_add_u32_e32 v8, s4, v8
	s_waitcnt lgkmcnt(6)
	v_perm_b32 v2, v9, v2, s5
	v_ashrrev_i32_e32 v9, 31, v8
	v_lshlrev_b64 v[8:9], 11, v[8:9]
	s_waitcnt lgkmcnt(0)
	v_perm_b32 v5, v0, v5, s5
	v_perm_b32 v4, v11, v4, s5
	v_perm_b32 v3, v10, v3, s5
	v_lshl_add_u64 v[6:7], v[6:7], 0, v[8:9]
	global_store_dwordx4 v[6:7], v[2:5], off
	s_barrier
	s_mov_b64 s[4:5], 0
